# cross attention: all 16 split-K q-partial loads issued together (one round trip) instead of four load/wait/accumulate groups
# baseline (speedup 1.0000x reference)
; __device__ __forceinline__ unsigned pk2(float lo, float hi) { const hf32x2 v = {lo, hi}; return __builtin_bit_cast(unsigned, __builtin_convertvector(v, hbf16x2)); }
; __device__ __forceinline__ void cross_attn_unit(PP p, unsigned char* shm, int u, int l) {
;     ...
;     const size_t rowq = (size_t)(b * SEQ + qt * 128 + 16 * w + fr);
;     float qs;
;     { const float* sp = (const float*)(p->ws + WS_SS) + ((size_t)(1 + 3 * l) * T + rowq) * 32 + quad * 8;
;       const f32x4 a0 = *(const f32x4*)sp, a1 = *(const f32x4*)(sp + 4);
;       float t = ((a0[0] + a0[1]) + (a0[2] + a0[3])) + ((a1[0] + a1[1]) + (a1[2] + a1[3]));
;       t += __shfl_xor(t, 16); t += __shfl_xor(t, 32);
;       qs = (0.08838834764831845f * 1.4426950408889634f) / sqrtf(t * (1.0f / D) + EPS); }
;     bf16x8 qf[4];
;     const bf16_t* qp = (const bf16_t*)(p->ws + WS_QP) + rowq * 512 + xh * 128 + quad * 8;
; #pragma unroll
;     for (int ks = 0; ks < 4; ++ks) {
;         float acc8[8], t8[8];
;         unpack8(*(const u32x4*)(qp + 32 * ks), acc8);
; #pragma unroll
;         for (int sp = 1; sp < 4; ++sp) { unpack8(*(const u32x4*)(qp + (size_t)sp * T * 512 + 32 * ks), t8);
; #pragma unroll
;             for (int e = 0; e < 8; ++e) acc8[e] += t8[e]; }
;         u32x4 pk; pk.x = pk2(acc8[0] * qs, acc8[1] * qs); pk.y = pk2(acc8[2] * qs, acc8[3] * qs); pk.z = pk2(acc8[4] * qs, acc8[5] * qs); pk.w = pk2(acc8[6] * qs, acc8[7] * qs);
.LBB0_1180:
	s_ashr_i32 s12, s2, 31
	s_lshr_b32 s13, s12, 26
	s_lshr_b32 s12, s12, 28
	s_mov_b64 s[8:9], s[0:1]
	s_add_i32 s13, s2, s13
	s_add_i32 s12, s2, s12
	v_mov_b32_e32 v21, v222
	s_ashr_i32 s17, s13, 6
	s_ashr_i32 s13, s12, 4
	s_load_dwordx2 s[8:9], s[8:9], 0x110
	s_lshr_b32 s12, s13, 30
	v_ashrrev_i32_e32 v0, 2, v21
	s_add_i32 s12, s13, s12
	v_and_b32_e32 v0, -16, v0
	v_and_b32_e32 v24, 15, v21
	s_and_b32 s12, s12, 0x1fffffc
	v_lshl_add_u32 v0, s17, 11, v0
	s_sub_i32 s12, s13, s12
	v_or_b32_e32 v0, v0, v24
	s_lshl_b32 s13, s13, 11
	v_subrev_u32_e32 v0, s13, v0
	v_add_u32_e32 v2, s3, v0
	s_mul_i32 s13, s28, 0x300000
	v_ashrrev_i32_e32 v3, 31, v2
	s_waitcnt lgkmcnt(0)
	s_add_u32 s20, s8, s13
	v_bfe_u32 v14, v21, 4, 2
	s_addc_u32 s21, s9, 0
	v_lshlrev_b64 v[4:5], 7, v[2:3]
	v_lshl_add_u64 v[4:5], s[20:21], 0, v[4:5]
	v_lshlrev_b32_e32 v6, 5, v14
	v_mov_b32_e32 v7, v1
	v_lshl_add_u64 v[4:5], v[4:5], 0, v[6:7]
	s_mov_b64 s[20:21], 0x35dc4000
	s_mov_b32 s13, 0x35dc4000
	v_lshl_add_u64 v[8:9], v[4:5], 0, s[20:21]
	v_add_co_u32_e32 v4, vcc, s13, v4
	s_lshl_b32 s12, s12, 7
	s_nop 0
	v_addc_co_u32_e32 v5, vcc, 0, v5, vcc
	global_load_dwordx4 v[4:7], v[4:5], off
	s_nop 0
	global_load_dwordx4 v[8:11], v[8:9], off offset:16
	v_lshlrev_b64 v[2:3], 10, v[2:3]
	s_ashr_i32 s13, s12, 31
	s_lshl_b64 s[12:13], s[12:13], 1
	v_lshl_add_u64 v[2:3], s[8:9], 0, v[2:3]
	v_lshlrev_b32_e32 v18, 4, v14
	v_mov_b32_e32 v19, v1
	v_lshl_add_u64 v[36:37], v[2:3], 0, s[12:13]
	v_lshlrev_b32_e32 v0, 3, v14
	v_lshl_add_u64 v[14:15], v[36:37], 0, v[18:19]
	s_mov_b32 s18, 0x369c4000
	s_add_u32 s8, s8, s16
	s_addc_u32 s9, s9, 0
	s_add_u32 s8, s8, s12
	s_addc_u32 s9, s9, s13
	v_lshl_add_u64 v[36:37], v[36:37], 0, v[0:1]
	s_add_i32 s2, s2, s66
	s_add_i32 s3, s3, s14
	s_waitcnt vmcnt(1)
	v_mov_b32_e32 v12, v4
	s_waitcnt vmcnt(0)
	v_mov_b32_e32 v13, v8
	v_mov_b32_e32 v8, v5
	v_pk_add_f32 v[4:5], v[12:13], v[8:9]
	v_mov_b32_e32 v8, v6
	v_mov_b32_e32 v9, v10
	v_mov_b32_e32 v10, v7
	v_pk_add_f32 v[6:7], v[8:9], v[10:11]
	s_nop 0
	v_pk_add_f32 v[4:5], v[4:5], v[6:7]
	v_and_b32_e32 v6, 64, v226
	v_add_f32_e32 v4, v4, v5
	v_xor_b32_e32 v5, 16, v226
	v_add_u32_e32 v6, 64, v6
	v_cmp_lt_i32_e32 vcc, v5, v6
	s_nop 1
	v_cndmask_b32_e32 v5, v226, v5, vcc
	v_lshlrev_b32_e32 v25, 2, v5
	ds_bpermute_b32 v5, v25, v4
	s_waitcnt lgkmcnt(0)
	v_add_f32_e32 v4, v4, v5
	v_xor_b32_e32 v5, 32, v226
	v_cmp_lt_i32_e32 vcc, v5, v6
	s_nop 1
	v_cndmask_b32_e32 v5, v226, v5, vcc
	v_lshlrev_b32_e32 v34, 2, v5
	ds_bpermute_b32 v5, v34, v4
	s_waitcnt lgkmcnt(0)
	v_add_f32_e32 v4, v4, v5
	v_fmamk_f32 v4, v4, 0x3a000000, v223
	v_cmp_gt_f32_e32 vcc, s11, v4
	v_mul_f32_e32 v5, 0x4f800000, v4
	s_nop 0
	v_cndmask_b32_e32 v4, v4, v5, vcc
	v_sqrt_f32_e32 v5, v4
	s_nop 0
	v_add_u32_e32 v6, -1, v5
	v_fma_f32 v7, -v6, v5, v4
	v_cmp_ge_f32_e64 s[38:39], 0, v7
	v_add_u32_e32 v7, 1, v5
	s_nop 0
	v_cndmask_b32_e64 v6, v5, v6, s[38:39]
	v_fma_f32 v5, -v7, v5, v4
	v_cmp_lt_f32_e64 s[38:39], 0, v5
	s_nop 1
	v_cndmask_b32_e64 v5, v6, v7, s[38:39]
	v_mul_f32_e32 v6, 0x37800000, v5
	v_cndmask_b32_e32 v5, v5, v6, vcc
	v_cmp_class_f32_e32 vcc, v4, v224
	s_nop 1
	v_cndmask_b32_e32 v4, v5, v4, vcc
	v_div_scale_f32 v5, s[20:21], v4, v4, s23
	v_rcp_f32_e32 v6, v5
	s_mov_b64 s[20:21], 0x369c4000
	v_lshl_add_u64 v[22:23], v[14:15], 0, s[20:21]
	v_fma_f32 v7, -v5, v6, 1.0
	v_fmac_f32_e32 v6, v7, v6
	v_div_scale_f32 v7, vcc, s23, v4, s23
	v_mul_f32_e32 v8, v7, v6
	v_fma_f32 v9, -v5, v8, v7
	v_fmac_f32_e32 v8, v9, v6
	v_fma_f32 v5, -v5, v8, v7
	v_div_fmas_f32 v5, v5, v6, v8
	v_add_co_u32_e32 v2, vcc, s18, v14
	s_mov_b32 s18, 0x371c4000
	s_nop 0
	v_addc_co_u32_e32 v3, vcc, 0, v15, vcc
	v_add_co_u32_e32 v38, vcc, s18, v14
	s_mov_b32 s18, 0x379c4000
	s_nop 0
	v_addc_co_u32_e32 v39, vcc, 0, v15, vcc
	v_add_co_u32_e32 v40, vcc, s18, v14
	s_mov_b32 s18, 0x381c4000
	s_nop 0
	v_addc_co_u32_e32 v41, vcc, 0, v15, vcc
	v_div_fixup_f32 v20, v5, v4, s23
	global_load_dwordx4 v[2:5], v[2:3], off
	v_add_co_u32_e32 v42, vcc, s18, v14
	global_load_dwordx4 v[6:9], v[38:39], off
	global_load_dwordx4 v[10:13], v[40:41], off
	v_addc_co_u32_e32 v43, vcc, 0, v15, vcc
	global_load_dwordx4 v[14:17], v[42:43], off
	global_load_dwordx4 v[130:133], v[22:23], off offset:64
	global_load_dwordx4 v[134:137], v[38:39], off offset:64
	global_load_dwordx4 v[138:141], v[40:41], off offset:64
	global_load_dwordx4 v[142:145], v[42:43], off offset:64
	global_load_dwordx4 v[146:149], v[22:23], off offset:128
	global_load_dwordx4 v[150:153], v[38:39], off offset:128
	global_load_dwordx4 v[154:157], v[40:41], off offset:128
	global_load_dwordx4 v[158:161], v[42:43], off offset:128
	global_load_dwordx4 v[162:165], v[22:23], off offset:192
	global_load_dwordx4 v[166:169], v[38:39], off offset:192
	global_load_dwordx4 v[170:173], v[40:41], off offset:192
	global_load_dwordx4 v[174:177], v[42:43], off offset:192
	s_waitcnt vmcnt(15)
	v_lshlrev_b32_e32 v26, 16, v2
	v_and_b32_e32 v27, 0xffff0000, v2
	s_waitcnt vmcnt(14)
	v_lshlrev_b32_e32 v28, 16, v6
	v_and_b32_e32 v29, 0xffff0000, v6
	v_pk_add_f32 v[26:27], v[26:27], v[28:29]
	s_waitcnt vmcnt(13)
	v_lshlrev_b32_e32 v28, 16, v10
	v_and_b32_e32 v29, 0xffff0000, v10
	v_pk_add_f32 v[26:27], v[26:27], v[28:29]
	s_waitcnt vmcnt(12)
; __device__ __forceinline__ unsigned pk2(float lo, float hi) { const hf32x2 v = {lo, hi}; return __builtin_bit_cast(unsigned, __builtin_convertvector(v, hbf16x2)); }
; __device__ __forceinline__ void cross_attn_unit(PP p, unsigned char* shm, int u, int l) {
;     ...
;     for (int ks = 0; ks < 4; ++ks) {
;         float acc8[8], t8[8];
;         unpack8(*(const u32x4*)(qp + 32 * ks), acc8);
; #pragma unroll
;         for (int sp = 1; sp < 4; ++sp) { unpack8(*(const u32x4*)(qp + (size_t)sp * T * 512 + 32 * ks), t8);
; #pragma unroll
;             for (int e = 0; e < 8; ++e) acc8[e] += t8[e]; }
;         u32x4 pk; pk.x = pk2(acc8[0] * qs, acc8[1] * qs); pk.y = pk2(acc8[2] * qs, acc8[3] * qs); pk.z = pk2(acc8[4] * qs, acc8[5] * qs); pk.w = pk2(acc8[6] * qs, acc8[7] * qs);
;         qf[ks] = __builtin_bit_cast(bf16x8, pk);
	v_lshlrev_b32_e32 v28, 16, v14
	v_and_b32_e32 v29, 0xffff0000, v14
	v_pk_add_f32 v[26:27], v[26:27], v[28:29]
	v_lshlrev_b32_e32 v6, 16, v7
	v_pk_mul_f32 v[26:27], v[20:21], v[26:27] op_sel_hi:[0,1]
	v_cvt_pk_bf16_f32 v2, v26, v27
	v_lshlrev_b32_e32 v26, 16, v3
	v_and_b32_e32 v27, 0xffff0000, v3
	v_and_b32_e32 v7, 0xffff0000, v7
	v_pk_add_f32 v[6:7], v[26:27], v[6:7]
	v_lshlrev_b32_e32 v10, 16, v11
	v_and_b32_e32 v11, 0xffff0000, v11
	v_pk_add_f32 v[6:7], v[6:7], v[10:11]
	v_lshlrev_b32_e32 v10, 16, v15
	v_and_b32_e32 v11, 0xffff0000, v15
	v_pk_add_f32 v[6:7], v[6:7], v[10:11]
	v_lshlrev_b32_e32 v10, 16, v8
	v_pk_mul_f32 v[6:7], v[20:21], v[6:7] op_sel_hi:[0,1]
	v_cvt_pk_bf16_f32 v3, v6, v7
	v_lshlrev_b32_e32 v6, 16, v4
	v_and_b32_e32 v7, 0xffff0000, v4
	v_and_b32_e32 v11, 0xffff0000, v8
	v_pk_add_f32 v[6:7], v[6:7], v[10:11]
	v_lshlrev_b32_e32 v10, 16, v12
	v_and_b32_e32 v11, 0xffff0000, v12
	v_pk_add_f32 v[6:7], v[6:7], v[10:11]
	v_lshlrev_b32_e32 v10, 16, v16
	v_and_b32_e32 v11, 0xffff0000, v16
	v_pk_add_f32 v[6:7], v[6:7], v[10:11]
	v_lshlrev_b32_e32 v8, 16, v9
	v_pk_mul_f32 v[6:7], v[20:21], v[6:7] op_sel_hi:[0,1]
	v_cvt_pk_bf16_f32 v4, v6, v7
	v_lshlrev_b32_e32 v6, 16, v5
	v_and_b32_e32 v7, 0xffff0000, v5
	v_and_b32_e32 v9, 0xffff0000, v9
	v_pk_add_f32 v[6:7], v[6:7], v[8:9]
	v_lshlrev_b32_e32 v8, 16, v13
	v_and_b32_e32 v9, 0xffff0000, v13
	v_pk_add_f32 v[6:7], v[6:7], v[8:9]
	v_lshlrev_b32_e32 v8, 16, v17
	v_and_b32_e32 v9, 0xffff0000, v17
	v_pk_add_f32 v[6:7], v[6:7], v[8:9]
	s_nop 0
	v_pk_mul_f32 v[6:7], v[20:21], v[6:7] op_sel_hi:[0,1]
	v_cvt_pk_bf16_f32 v5, v6, v7
	s_waitcnt vmcnt(8)
	v_mov_b32_e32 v6, v130
	v_mov_b32_e32 v7, v131
	v_mov_b32_e32 v8, v132
	v_mov_b32_e32 v9, v133
	v_mov_b32_e32 v10, v134
	v_mov_b32_e32 v11, v135
	v_mov_b32_e32 v12, v136
	v_mov_b32_e32 v13, v137
	v_mov_b32_e32 v14, v138
	v_mov_b32_e32 v15, v139
	v_mov_b32_e32 v16, v140
	v_mov_b32_e32 v17, v141
	v_mov_b32_e32 v26, v142
	v_mov_b32_e32 v27, v143
	v_mov_b32_e32 v28, v144
	v_mov_b32_e32 v29, v145
	v_lshlrev_b32_e32 v30, 16, v6
	v_and_b32_e32 v31, 0xffff0000, v6
	v_lshlrev_b32_e32 v32, 16, v10
	v_and_b32_e32 v33, 0xffff0000, v10
	v_pk_add_f32 v[30:31], v[30:31], v[32:33]
	v_lshlrev_b32_e32 v32, 16, v14
	v_and_b32_e32 v33, 0xffff0000, v14
	v_pk_add_f32 v[30:31], v[30:31], v[32:33]
	v_lshlrev_b32_e32 v32, 16, v26
	v_and_b32_e32 v33, 0xffff0000, v26
	v_pk_add_f32 v[30:31], v[30:31], v[32:33]
	v_lshlrev_b32_e32 v10, 16, v11
	v_pk_mul_f32 v[30:31], v[20:21], v[30:31] op_sel_hi:[0,1]
	v_cvt_pk_bf16_f32 v6, v30, v31
	v_lshlrev_b32_e32 v30, 16, v7
	v_and_b32_e32 v31, 0xffff0000, v7
	v_and_b32_e32 v11, 0xffff0000, v11
	v_pk_add_f32 v[10:11], v[30:31], v[10:11]
	v_lshlrev_b32_e32 v14, 16, v15
	v_and_b32_e32 v15, 0xffff0000, v15
	v_pk_add_f32 v[10:11], v[10:11], v[14:15]
	v_lshlrev_b32_e32 v14, 16, v27
	v_and_b32_e32 v15, 0xffff0000, v27
	v_pk_add_f32 v[10:11], v[10:11], v[14:15]
	v_lshlrev_b32_e32 v14, 16, v12
	v_pk_mul_f32 v[10:11], v[20:21], v[10:11] op_sel_hi:[0,1]
	v_cvt_pk_bf16_f32 v7, v10, v11
	v_lshlrev_b32_e32 v10, 16, v8
	v_and_b32_e32 v11, 0xffff0000, v8
	v_and_b32_e32 v15, 0xffff0000, v12
	v_pk_add_f32 v[10:11], v[10:11], v[14:15]
	v_lshlrev_b32_e32 v14, 16, v16
	v_and_b32_e32 v15, 0xffff0000, v16
	v_pk_add_f32 v[10:11], v[10:11], v[14:15]
	v_lshlrev_b32_e32 v14, 16, v28
	v_and_b32_e32 v15, 0xffff0000, v28
	v_pk_add_f32 v[10:11], v[10:11], v[14:15]
	v_lshlrev_b32_e32 v12, 16, v13
	v_pk_mul_f32 v[10:11], v[20:21], v[10:11] op_sel_hi:[0,1]
	v_cvt_pk_bf16_f32 v8, v10, v11
	v_lshlrev_b32_e32 v10, 16, v9
	v_and_b32_e32 v11, 0xffff0000, v9
	v_and_b32_e32 v13, 0xffff0000, v13
	v_pk_add_f32 v[10:11], v[10:11], v[12:13]
	v_lshlrev_b32_e32 v12, 16, v17
	v_and_b32_e32 v13, 0xffff0000, v17
	v_pk_add_f32 v[10:11], v[10:11], v[12:13]
	v_lshlrev_b32_e32 v12, 16, v29
	v_and_b32_e32 v13, 0xffff0000, v29
	v_pk_add_f32 v[10:11], v[10:11], v[12:13]
	s_nop 0
	v_pk_mul_f32 v[10:11], v[20:21], v[10:11] op_sel_hi:[0,1]
	v_cvt_pk_bf16_f32 v9, v10, v11
	s_waitcnt vmcnt(4)
	v_mov_b32_e32 v10, v146
	v_mov_b32_e32 v11, v147
	v_mov_b32_e32 v12, v148
	v_mov_b32_e32 v13, v149
	v_mov_b32_e32 v14, v150
	v_mov_b32_e32 v15, v151
	v_mov_b32_e32 v16, v152
	v_mov_b32_e32 v17, v153
	v_mov_b32_e32 v26, v154
	v_mov_b32_e32 v27, v155
	v_mov_b32_e32 v28, v156
	v_mov_b32_e32 v29, v157
	v_mov_b32_e32 v30, v158
	v_mov_b32_e32 v31, v159
	v_mov_b32_e32 v32, v160
	v_mov_b32_e32 v33, v161
	v_lshlrev_b32_e32 v44, 16, v10
	v_and_b32_e32 v45, 0xffff0000, v10
	v_lshlrev_b32_e32 v46, 16, v14
	v_and_b32_e32 v47, 0xffff0000, v14
	v_pk_add_f32 v[44:45], v[44:45], v[46:47]
	v_lshlrev_b32_e32 v46, 16, v26
	v_and_b32_e32 v47, 0xffff0000, v26
	v_pk_add_f32 v[44:45], v[44:45], v[46:47]
	v_lshlrev_b32_e32 v46, 16, v30
	v_and_b32_e32 v47, 0xffff0000, v30
	v_pk_add_f32 v[44:45], v[44:45], v[46:47]
	v_lshlrev_b32_e32 v14, 16, v15
	v_pk_mul_f32 v[44:45], v[20:21], v[44:45] op_sel_hi:[0,1]
	v_cvt_pk_bf16_f32 v10, v44, v45
	v_lshlrev_b32_e32 v44, 16, v11
	v_and_b32_e32 v45, 0xffff0000, v11
	v_and_b32_e32 v15, 0xffff0000, v15
	v_pk_add_f32 v[14:15], v[44:45], v[14:15]
	v_lshlrev_b32_e32 v26, 16, v27
	v_and_b32_e32 v27, 0xffff0000, v27
	v_pk_add_f32 v[14:15], v[14:15], v[26:27]
	v_lshlrev_b32_e32 v26, 16, v31
	v_and_b32_e32 v27, 0xffff0000, v31
	v_pk_add_f32 v[14:15], v[14:15], v[26:27]
	v_lshlrev_b32_e32 v26, 16, v16
	v_pk_mul_f32 v[14:15], v[20:21], v[14:15] op_sel_hi:[0,1]
	v_cvt_pk_bf16_f32 v11, v14, v15
	v_lshlrev_b32_e32 v14, 16, v12
	v_and_b32_e32 v15, 0xffff0000, v12
	v_and_b32_e32 v27, 0xffff0000, v16
	v_pk_add_f32 v[14:15], v[14:15], v[26:27]
	v_lshlrev_b32_e32 v26, 16, v28
	v_and_b32_e32 v27, 0xffff0000, v28
	v_pk_add_f32 v[14:15], v[14:15], v[26:27]
	v_lshlrev_b32_e32 v26, 16, v32
	v_and_b32_e32 v27, 0xffff0000, v32
	v_pk_add_f32 v[14:15], v[14:15], v[26:27]
	v_lshlrev_b32_e32 v16, 16, v17
	v_pk_mul_f32 v[14:15], v[20:21], v[14:15] op_sel_hi:[0,1]
	v_cvt_pk_bf16_f32 v12, v14, v15
	v_lshlrev_b32_e32 v14, 16, v13
	v_and_b32_e32 v15, 0xffff0000, v13
	v_and_b32_e32 v17, 0xffff0000, v17
	v_pk_add_f32 v[14:15], v[14:15], v[16:17]
	v_lshlrev_b32_e32 v16, 16, v29
	v_and_b32_e32 v17, 0xffff0000, v29
	v_pk_add_f32 v[14:15], v[14:15], v[16:17]
	v_lshlrev_b32_e32 v16, 16, v33
	v_and_b32_e32 v17, 0xffff0000, v33
	v_pk_add_f32 v[14:15], v[14:15], v[16:17]
	s_nop 0
	v_pk_mul_f32 v[14:15], v[20:21], v[14:15] op_sel_hi:[0,1]
	v_cvt_pk_bf16_f32 v13, v14, v15
	s_waitcnt vmcnt(0)
; __device__ __forceinline__ unsigned pk2(float lo, float hi) { const hf32x2 v = {lo, hi}; return __builtin_bit_cast(unsigned, __builtin_convertvector(v, hbf16x2)); }
; __device__ __forceinline__ void cross_attn_unit(PP p, unsigned char* shm, int u, int l) {
;     ...
;         unpack8(*(const u32x4*)(qp + 32 * ks), acc8);
; #pragma unroll
;         for (int sp = 1; sp < 4; ++sp) { unpack8(*(const u32x4*)(qp + (size_t)sp * T * 512 + 32 * ks), t8);
; #pragma unroll
;             for (int e = 0; e < 8; ++e) acc8[e] += t8[e]; }
;         u32x4 pk; pk.x = pk2(acc8[0] * qs, acc8[1] * qs); pk.y = pk2(acc8[2] * qs, acc8[3] * qs); pk.z = pk2(acc8[4] * qs, acc8[5] * qs); pk.w = pk2(acc8[6] * qs, acc8[7] * qs);
;         qf[ks] = __builtin_bit_cast(bf16x8, pk);
;     }
;     {
;         u32x4 kq[8], vq[8];
; #pragma unroll
;         for (int i = 0; i < 8; ++i) { const int m = 2 * (tid >> 4) + (i & 1) + 64 * (i >> 1), ch = tid & 15;
;             const bf16_t* rowp = kvb + (size_t)(b * 256 + m) * 4096 + l * 1024 + xh * 128 + ch * 8; kq[i] = *(const u32x4*)rowp; vq[i] = *(const u32x4*)(rowp + 512); }
; #pragma unroll
;         for (int i = 0; i < 8; ++i) { const int m = 2 * (tid >> 4) + (i & 1) + 64 * (i >> 1), ch = tid & 15; *(u32x4*)(Ks + m * 136 + ch * 8) = kq[i]; }
	v_mov_b32_e32 v14, v162
	v_mov_b32_e32 v15, v163
	v_mov_b32_e32 v16, v164
	v_mov_b32_e32 v17, v165
	v_mov_b32_e32 v26, v166
	v_mov_b32_e32 v27, v167
	v_mov_b32_e32 v28, v168
	v_mov_b32_e32 v29, v169
	v_mov_b32_e32 v30, v170
	v_mov_b32_e32 v31, v171
	v_mov_b32_e32 v32, v172
	v_mov_b32_e32 v33, v173
	v_mov_b32_e32 v38, v174
	v_mov_b32_e32 v39, v175
	v_mov_b32_e32 v40, v176
	v_mov_b32_e32 v41, v177
	s_nop 0
	v_lshlrev_b32_e32 v22, 16, v14
	v_and_b32_e32 v23, 0xffff0000, v14
	v_lshlrev_b32_e32 v42, 16, v26
	v_and_b32_e32 v43, 0xffff0000, v26
	v_pk_add_f32 v[22:23], v[22:23], v[42:43]
	v_lshlrev_b32_e32 v42, 16, v30
	v_and_b32_e32 v43, 0xffff0000, v30
	v_pk_add_f32 v[22:23], v[22:23], v[42:43]
	v_lshlrev_b32_e32 v42, 16, v38
	v_and_b32_e32 v43, 0xffff0000, v38
	v_pk_add_f32 v[22:23], v[22:23], v[42:43]
	v_lshlrev_b32_e32 v26, 16, v27
	v_pk_mul_f32 v[22:23], v[20:21], v[22:23] op_sel_hi:[0,1]
	v_cvt_pk_bf16_f32 v14, v22, v23
	v_lshlrev_b32_e32 v22, 16, v15
	v_and_b32_e32 v23, 0xffff0000, v15
	v_and_b32_e32 v27, 0xffff0000, v27
	v_pk_add_f32 v[22:23], v[22:23], v[26:27]
	v_lshlrev_b32_e32 v26, 16, v31
	v_and_b32_e32 v27, 0xffff0000, v31
	v_pk_add_f32 v[22:23], v[22:23], v[26:27]
	v_lshlrev_b32_e32 v26, 16, v39
	v_and_b32_e32 v27, 0xffff0000, v39
	v_pk_add_f32 v[22:23], v[22:23], v[26:27]
	v_lshlrev_b32_e32 v26, 16, v28
	v_pk_mul_f32 v[22:23], v[20:21], v[22:23] op_sel_hi:[0,1]
	v_cvt_pk_bf16_f32 v15, v22, v23
	v_lshlrev_b32_e32 v22, 16, v16
	v_and_b32_e32 v23, 0xffff0000, v16
	v_and_b32_e32 v27, 0xffff0000, v28
	v_pk_add_f32 v[22:23], v[22:23], v[26:27]
	v_lshlrev_b32_e32 v26, 16, v32
	v_and_b32_e32 v27, 0xffff0000, v32
	v_pk_add_f32 v[22:23], v[22:23], v[26:27]
	v_lshlrev_b32_e32 v26, 16, v40
	v_and_b32_e32 v27, 0xffff0000, v40
	v_pk_add_f32 v[22:23], v[22:23], v[26:27]
	v_lshlrev_b32_e32 v26, 16, v29
	v_pk_mul_f32 v[22:23], v[20:21], v[22:23] op_sel_hi:[0,1]
	v_cvt_pk_bf16_f32 v16, v22, v23
	v_lshlrev_b32_e32 v22, 16, v17
	v_and_b32_e32 v23, 0xffff0000, v17
	v_and_b32_e32 v27, 0xffff0000, v29
	v_pk_add_f32 v[22:23], v[22:23], v[26:27]
	v_lshlrev_b32_e32 v26, 16, v33
	v_and_b32_e32 v27, 0xffff0000, v33
	v_pk_add_f32 v[22:23], v[22:23], v[26:27]
	v_lshlrev_b32_e32 v26, 16, v41
	v_and_b32_e32 v27, 0xffff0000, v41
	v_pk_add_f32 v[22:23], v[22:23], v[26:27]
	v_ashrrev_i32_e32 v27, 3, v21
	v_pk_mul_f32 v[22:23], v[20:21], v[22:23] op_sel_hi:[0,1]
	v_lshlrev_b32_e32 v21, 3, v21
	v_and_b32_e32 v19, -2, v27
	v_and_b32_e32 v26, 0x78, v21
	v_cvt_pk_bf16_f32 v17, v22, v23
	v_lshl_add_u32 v20, s17, 8, v19
	v_lshlrev_b32_e32 v22, 1, v26
	v_mov_b32_e32 v23, v1
	v_lshl_add_u64 v[28:29], s[8:9], 0, v[22:23]
	s_mov_b64 s[8:9], 0x28ec0000
	v_ashrrev_i32_e32 v21, 31, v20
	v_lshl_add_u64 v[32:33], v[28:29], 0, s[8:9]
	v_lshlrev_b64 v[28:29], 13, v[20:21]
	v_or_b32_e32 v42, 1, v20
	v_add_u32_e32 v50, 64, v20
	v_add_u32_e32 v58, 0x41, v20
	v_add_u32_e32 v66, 0x80, v20
	v_add_u32_e32 v74, 0x81, v20
	v_add_u32_e32 v82, 0xc0, v20
	v_add_u32_e32 v20, 0xc1, v20
	v_ashrrev_i32_e32 v43, 31, v42
	v_ashrrev_i32_e32 v51, 31, v50
	v_ashrrev_i32_e32 v59, 31, v58
	v_ashrrev_i32_e32 v67, 31, v66
	v_ashrrev_i32_e32 v75, 31, v74
	v_ashrrev_i32_e32 v83, 31, v82
	v_ashrrev_i32_e32 v21, 31, v20
	v_lshlrev_b64 v[42:43], 13, v[42:43]
	v_lshlrev_b64 v[50:51], 13, v[50:51]
	v_lshlrev_b64 v[58:59], 13, v[58:59]
	v_lshlrev_b64 v[66:67], 13, v[66:67]
	v_lshlrev_b64 v[74:75], 13, v[74:75]
	v_lshlrev_b64 v[82:83], 13, v[82:83]
	v_lshlrev_b64 v[20:21], 13, v[20:21]
	v_lshl_add_u64 v[38:39], v[32:33], 0, v[28:29]
	v_lshl_add_u64 v[46:47], v[32:33], 0, v[42:43]
	v_lshl_add_u64 v[54:55], v[32:33], 0, v[50:51]
	v_lshl_add_u64 v[62:63], v[32:33], 0, v[58:59]
	v_lshl_add_u64 v[70:71], v[32:33], 0, v[66:67]
	v_lshl_add_u64 v[78:79], v[32:33], 0, v[74:75]
	v_lshl_add_u64 v[86:87], v[32:33], 0, v[82:83]
	v_lshl_add_u64 v[20:21], v[32:33], 0, v[20:21]
	global_load_dwordx4 v[28:31], v[38:39], off
	s_nop 0
	global_load_dwordx4 v[38:41], v[38:39], off offset:1024
	s_nop 0
	global_load_dwordx4 v[42:45], v[46:47], off
	s_nop 0
	global_load_dwordx4 v[46:49], v[46:47], off offset:1024
	s_nop 0
	global_load_dwordx4 v[50:53], v[54:55], off
	s_nop 0
	global_load_dwordx4 v[54:57], v[54:55], off offset:1024
	s_nop 0
	global_load_dwordx4 v[58:61], v[62:63], off
	s_nop 0
	global_load_dwordx4 v[62:65], v[62:63], off offset:1024
	s_nop 0
	global_load_dwordx4 v[66:69], v[70:71], off
	s_nop 0
	global_load_dwordx4 v[70:73], v[70:71], off offset:1024
	s_nop 0
	global_load_dwordx4 v[74:77], v[78:79], off
	s_nop 0
	global_load_dwordx4 v[78:81], v[78:79], off offset:1024
	s_nop 0
	global_load_dwordx4 v[82:85], v[86:87], off
	s_nop 0
	global_load_dwordx4 v[86:89], v[86:87], off offset:1024
	s_nop 0
	global_load_dwordx4 v[90:93], v[20:21], off
	global_load_dwordx4 v[94:97], v[20:21], off offset:1024
	v_add_u32_e32 v20, 0, v22
	v_mad_u64_u32 v[22:23], s[8:9], v19, s24, v[20:21]
	v_or_b32_e32 v21, 1, v27
	v_mad_u64_u32 v[20:21], s[8:9], v21, s24, v[20:21]
	s_add_i32 s8, 0, 0x11000
	v_lshlrev_b32_e32 v19, 1, v19
	s_cmpk_gt_i32 s2, 0xff
	s_waitcnt vmcnt(15)
	ds_write_b128 v22, v[28:31]
	s_waitcnt vmcnt(13)
	ds_write_b128 v20, v[42:45]
	s_waitcnt vmcnt(11)
	ds_write_b128 v22, v[50:53] offset:17408
	s_waitcnt vmcnt(9)
	ds_write_b128 v20, v[58:61] offset:17408
	s_waitcnt vmcnt(7)
	ds_write_b128 v22, v[66:69] offset:34816
	s_waitcnt vmcnt(5)
	ds_write_b128 v20, v[74:77] offset:34816
	s_waitcnt vmcnt(3)
	ds_write_b128 v22, v[82:85] offset:52224
	s_waitcnt vmcnt(1)
; template <int HD, bool DIL>
; __device__ __forceinline__ void attn_compute(const bf16_t* Ks, const bf16_t* Vt, const bf16x8 (&qf)[HD / 32], int a, int quad, int fr,
;                                              const float* biasT, int kmin, f32x4 (&oacc)[HD / 16], float& mx_out, float& den_out) {
;     ...
;     for (int nt = 0; nt < 16; ++nt) {
;         s[nt] = (f32x4){0.f, 0.f, 0.f, 0.f};
; #pragma unroll
;         for (int ks = 0; ks < HD / 32; ++ks) {
;             const bf16x8 kf = *(const bf16x8*)(Ks + (16 * nt + fr) * (HD + 8) + quad * 8 + 32 * ks);
;             s[nt] = __builtin_amdgcn_mfma_f32_16x16x32_bf16(kf, qf[ks], s[nt], 0, 0, 0);
;         }
;     }
; __device__ __forceinline__ void cross_attn_unit(PP p, unsigned char* shm, int u, int l) {
;     ...
;         for (int i = 0; i < 8; ++i) { const int m = 2 * (tid >> 4) + (i & 1) + 64 * (i >> 1), ch = tid & 15; *(u32x4*)(Ks + m * 136 + ch * 8) = kq[i]; }
; #pragma unroll
;         for (int i = 0; i < 8; i += 2) { const int m = 2 * (tid >> 4) + 64 * (i >> 1), ch = tid & 15; vt_store_pair(Vt, ch * 8, m, vq[i], vq[i + 1]); }
;     }
;     __syncthreads();
	ds_write_b128 v20, v[90:93] offset:52224
	v_mul_u32_u24_e32 v20, 0x218, v26
	v_add3_u32 v19, s8, v20, v19
	v_and_b32_e32 v20, 0xffff, v38
	v_and_b32_e32 v30, 0xffff, v54
	v_lshl_or_b32 v20, v46, 16, v20
	v_lshl_or_b32 v30, v62, 16, v30
	v_lshrrev_b32_e32 v21, 16, v38
	ds_write2_b32 v19, v20, v30 offset1:32
	v_lshrrev_b32_e32 v20, 16, v54
	v_and_or_b32 v21, v46, s10, v21
	v_and_or_b32 v20, v62, s10, v20
	v_and_b32_e32 v22, 0xffff, v39
	ds_write2_b32 v19, v21, v20 offset0:134 offset1:166
	v_and_b32_e32 v20, 0xffff, v55
	v_lshl_or_b32 v22, v47, 16, v22
	v_lshl_or_b32 v20, v63, 16, v20
	v_add_u32_e32 v21, 0x400, v19
	v_lshrrev_b32_e32 v23, 16, v39
	ds_write2_b32 v21, v22, v20 offset0:12 offset1:44
	v_lshrrev_b32_e32 v20, 16, v55
	v_and_or_b32 v23, v47, s10, v23
	v_and_or_b32 v20, v63, s10, v20
	v_and_b32_e32 v26, 0xffff, v40
	ds_write2_b32 v21, v23, v20 offset0:146 offset1:178
	v_and_b32_e32 v20, 0xffff, v56
	v_lshl_or_b32 v26, v48, 16, v26
	v_lshl_or_b32 v20, v64, 16, v20
	v_add_u32_e32 v22, 0x800, v19
	v_lshrrev_b32_e32 v27, 16, v40
	ds_write2_b32 v22, v26, v20 offset0:24 offset1:56
	v_lshrrev_b32_e32 v20, 16, v56
	v_and_or_b32 v27, v48, s10, v27
	v_and_or_b32 v20, v64, s10, v20
	v_and_b32_e32 v28, 0xffff, v41
	ds_write2_b32 v22, v27, v20 offset0:158 offset1:190
	v_and_b32_e32 v20, 0xffff, v57
	v_lshl_or_b32 v28, v49, 16, v28
	v_lshl_or_b32 v20, v65, 16, v20
	v_add_u32_e32 v23, 0xc00, v19
	v_lshrrev_b32_e32 v29, 16, v41
	ds_write2_b32 v23, v28, v20 offset0:36 offset1:68
	v_lshrrev_b32_e32 v20, 16, v57
	v_and_or_b32 v29, v49, s10, v29
	v_and_or_b32 v20, v65, s10, v20
	ds_write2_b32 v23, v29, v20 offset0:170 offset1:202
	v_and_b32_e32 v20, 0xffff, v70
	v_and_b32_e32 v33, 0xffff, v86
	v_lshl_or_b32 v20, v78, 16, v20
	s_waitcnt vmcnt(0)
	v_lshl_or_b32 v33, v94, 16, v33
	v_lshrrev_b32_e32 v26, 16, v70
	ds_write2_b32 v19, v20, v33 offset0:64 offset1:96
	v_lshrrev_b32_e32 v20, 16, v86
	v_and_or_b32 v26, v78, s10, v26
	v_and_or_b32 v20, v94, s10, v20
	v_and_b32_e32 v27, 0xffff, v71
	ds_write2_b32 v19, v26, v20 offset0:198 offset1:230
	v_and_b32_e32 v20, 0xffff, v87
	v_lshl_or_b32 v27, v79, 16, v27
	v_lshl_or_b32 v20, v95, 16, v20
	v_lshrrev_b32_e32 v28, 16, v71
	ds_write2_b32 v21, v27, v20 offset0:76 offset1:108
	v_lshrrev_b32_e32 v20, 16, v87
	v_and_or_b32 v28, v79, s10, v28
	v_and_or_b32 v20, v95, s10, v20
	v_and_b32_e32 v29, 0xffff, v72
	ds_write2_b32 v21, v28, v20 offset0:210 offset1:242
	v_and_b32_e32 v20, 0xffff, v88
	v_lshl_or_b32 v29, v80, 16, v29
	v_lshl_or_b32 v20, v96, 16, v20
	v_lshrrev_b32_e32 v30, 16, v72
	ds_write2_b32 v22, v29, v20 offset0:88 offset1:120
	v_lshrrev_b32_e32 v20, 16, v88
	v_and_or_b32 v30, v80, s10, v30
	v_and_or_b32 v20, v96, s10, v20
	v_and_b32_e32 v31, 0xffff, v73
	ds_write2_b32 v22, v30, v20 offset0:222 offset1:254
	v_and_b32_e32 v20, 0xffff, v89
	v_lshl_or_b32 v31, v81, 16, v31
	v_lshl_or_b32 v20, v97, 16, v20
	v_lshrrev_b32_e32 v32, 16, v73
	ds_write2_b32 v23, v31, v20 offset0:100 offset1:132
	v_lshrrev_b32_e32 v20, 16, v89
	v_and_or_b32 v32, v81, s10, v32
	v_and_or_b32 v20, v97, s10, v20
	v_add_u32_e32 v19, 0xe00, v19
	ds_write2_b32 v19, v32, v20 offset0:106 offset1:138
	v_mul_u32_u24_e32 v19, 0x110, v24
	v_add3_u32 v22, 0, v18, v19
	s_waitcnt lgkmcnt(0)
	s_barrier
	ds_read_b128 v[18:21], v22
	ds_read_b128 v[26:29], v22 offset:64
	s_waitcnt lgkmcnt(1)
	v_mfma_f32_16x16x32_bf16 v[18:21], v[18:21], v[2:5], 0
	ds_read_b128 v[30:33], v22 offset:4416
	ds_read_b128 v[38:41], v22 offset:8768
	ds_read_b128 v[42:45], v22 offset:13120
	s_waitcnt lgkmcnt(3)
	v_mfma_f32_16x16x32_bf16 v[18:21], v[26:29], v[6:9], v[18:21]
	ds_read_b128 v[26:29], v22 offset:128
	ds_read_b128 v[46:49], v22 offset:17472
	ds_read_b128 v[50:53], v22 offset:21824
	s_waitcnt lgkmcnt(2)
	v_mfma_f32_16x16x32_bf16 v[18:21], v[26:29], v[10:13], v[18:21]
	ds_read_b128 v[26:29], v22 offset:192
	ds_read_b128 v[54:57], v22 offset:26176
	ds_read_b128 v[58:61], v22 offset:30528
	s_waitcnt lgkmcnt(2)
	v_mfma_f32_16x16x32_bf16 v[18:21], v[26:29], v[14:17], v[18:21]
	ds_read_b128 v[26:29], v22 offset:4352
	ds_read_b128 v[62:65], v22 offset:34880
	ds_read_b128 v[66:69], v22 offset:39232
	s_waitcnt lgkmcnt(2)
	v_mfma_f32_16x16x32_bf16 v[26:29], v[26:29], v[2:5], 0
	ds_read_b128 v[70:73], v22 offset:43584
	ds_read_b128 v[74:77], v22 offset:47936
	ds_read_b128 v[78:81], v22 offset:52288
	v_mfma_f32_16x16x32_bf16 v[26:29], v[30:33], v[6:9], v[26:29]
	ds_read_b128 v[30:33], v22 offset:4480
	ds_read_b128 v[82:85], v22 offset:56640
	ds_read_b128 v[86:89], v22 offset:60992
	s_waitcnt lgkmcnt(2)
	v_mfma_f32_16x16x32_bf16 v[26:29], v[30:33], v[10:13], v[26:29]
	ds_read_b128 v[30:33], v22 offset:4544
	s_waitcnt lgkmcnt(0)
	v_mfma_f32_16x16x32_bf16 v[26:29], v[30:33], v[14:17], v[26:29]
	ds_read_b128 v[30:33], v22 offset:8704
	s_waitcnt lgkmcnt(0)
	v_mfma_f32_16x16x32_bf16 v[30:33], v[30:33], v[2:5], 0
	v_mfma_f32_16x16x32_bf16 v[30:33], v[38:41], v[6:9], v[30:33]
	ds_read_b128 v[38:41], v22 offset:8832
	s_waitcnt lgkmcnt(0)
	v_mfma_f32_16x16x32_bf16 v[30:33], v[38:41], v[10:13], v[30:33]
	ds_read_b128 v[38:41], v22 offset:8896
	s_waitcnt lgkmcnt(0)
	v_mfma_f32_16x16x32_bf16 v[30:33], v[38:41], v[14:17], v[30:33]
	ds_read_b128 v[38:41], v22 offset:13056
	s_waitcnt lgkmcnt(0)
	v_mfma_f32_16x16x32_bf16 v[38:41], v[38:41], v[2:5], 0
	v_mfma_f32_16x16x32_bf16 v[38:41], v[42:45], v[6:9], v[38:41]
	ds_read_b128 v[42:45], v22 offset:13184
	s_waitcnt lgkmcnt(0)
	v_mfma_f32_16x16x32_bf16 v[38:41], v[42:45], v[10:13], v[38:41]
	ds_read_b128 v[42:45], v22 offset:13248
	s_waitcnt lgkmcnt(0)
	v_mfma_f32_16x16x32_bf16 v[38:41], v[42:45], v[14:17], v[38:41]
	ds_read_b128 v[42:45], v22 offset:17408
	s_waitcnt lgkmcnt(0)
; template <int HD, bool DIL>
; __device__ __forceinline__ void attn_compute(const bf16_t* Ks, const bf16_t* Vt, const bf16x8 (&qf)[HD / 32], int a, int quad, int fr,
;                                              const float* biasT, int kmin, f32x4 (&oacc)[HD / 16], float& mx_out, float& den_out) {
;     ...
;     for (int nt = 0; nt < 16; ++nt) {
;         s[nt] = (f32x4){0.f, 0.f, 0.f, 0.f};
; #pragma unroll
;         for (int ks = 0; ks < HD / 32; ++ks) {
;             const bf16x8 kf = *(const bf16x8*)(Ks + (16 * nt + fr) * (HD + 8) + quad * 8 + 32 * ks);
;             s[nt] = __builtin_amdgcn_mfma_f32_16x16x32_bf16(kf, qf[ks], s[nt], 0, 0, 0);
;         }
;     }
	v_mfma_f32_16x16x32_bf16 v[42:45], v[42:45], v[2:5], 0
	v_mfma_f32_16x16x32_bf16 v[42:45], v[46:49], v[6:9], v[42:45]
	ds_read_b128 v[46:49], v22 offset:17536
	s_waitcnt lgkmcnt(0)
	v_mfma_f32_16x16x32_bf16 v[42:45], v[46:49], v[10:13], v[42:45]
	ds_read_b128 v[46:49], v22 offset:17600
	s_waitcnt lgkmcnt(0)
	v_mfma_f32_16x16x32_bf16 v[42:45], v[46:49], v[14:17], v[42:45]
	ds_read_b128 v[46:49], v22 offset:21760
	s_waitcnt lgkmcnt(0)
	v_mfma_f32_16x16x32_bf16 v[46:49], v[46:49], v[2:5], 0
	v_mfma_f32_16x16x32_bf16 v[46:49], v[50:53], v[6:9], v[46:49]
	ds_read_b128 v[50:53], v22 offset:21888
	s_waitcnt lgkmcnt(0)
	v_mfma_f32_16x16x32_bf16 v[46:49], v[50:53], v[10:13], v[46:49]
	ds_read_b128 v[50:53], v22 offset:21952
	s_waitcnt lgkmcnt(0)
	v_mfma_f32_16x16x32_bf16 v[46:49], v[50:53], v[14:17], v[46:49]
	ds_read_b128 v[50:53], v22 offset:26112
	s_waitcnt lgkmcnt(0)
	v_mfma_f32_16x16x32_bf16 v[50:53], v[50:53], v[2:5], 0
	v_mfma_f32_16x16x32_bf16 v[50:53], v[54:57], v[6:9], v[50:53]
	ds_read_b128 v[54:57], v22 offset:26240
	s_waitcnt lgkmcnt(0)
	v_mfma_f32_16x16x32_bf16 v[50:53], v[54:57], v[10:13], v[50:53]
	ds_read_b128 v[54:57], v22 offset:26304
	s_waitcnt lgkmcnt(0)
	v_mfma_f32_16x16x32_bf16 v[50:53], v[54:57], v[14:17], v[50:53]
	ds_read_b128 v[54:57], v22 offset:30464
	s_waitcnt lgkmcnt(0)
	v_mfma_f32_16x16x32_bf16 v[54:57], v[54:57], v[2:5], 0
	v_mfma_f32_16x16x32_bf16 v[54:57], v[58:61], v[6:9], v[54:57]
	ds_read_b128 v[58:61], v22 offset:30592
	s_waitcnt lgkmcnt(0)
	v_mfma_f32_16x16x32_bf16 v[54:57], v[58:61], v[10:13], v[54:57]
	ds_read_b128 v[58:61], v22 offset:30656
	s_waitcnt lgkmcnt(0)
	v_mfma_f32_16x16x32_bf16 v[54:57], v[58:61], v[14:17], v[54:57]
	ds_read_b128 v[58:61], v22 offset:34816
	s_waitcnt lgkmcnt(0)
	v_mfma_f32_16x16x32_bf16 v[58:61], v[58:61], v[2:5], 0
	v_mfma_f32_16x16x32_bf16 v[58:61], v[62:65], v[6:9], v[58:61]
	ds_read_b128 v[62:65], v22 offset:34944
	s_waitcnt lgkmcnt(0)
	v_mfma_f32_16x16x32_bf16 v[58:61], v[62:65], v[10:13], v[58:61]
	ds_read_b128 v[62:65], v22 offset:35008
	s_waitcnt lgkmcnt(0)
	v_mfma_f32_16x16x32_bf16 v[58:61], v[62:65], v[14:17], v[58:61]
	ds_read_b128 v[62:65], v22 offset:39168
	s_waitcnt lgkmcnt(0)
	v_mfma_f32_16x16x32_bf16 v[62:65], v[62:65], v[2:5], 0
	v_mfma_f32_16x16x32_bf16 v[62:65], v[66:69], v[6:9], v[62:65]
	ds_read_b128 v[66:69], v22 offset:39296
	s_waitcnt lgkmcnt(0)
	v_mfma_f32_16x16x32_bf16 v[62:65], v[66:69], v[10:13], v[62:65]
	ds_read_b128 v[66:69], v22 offset:39360
	s_waitcnt lgkmcnt(0)
	v_mfma_f32_16x16x32_bf16 v[62:65], v[66:69], v[14:17], v[62:65]
	ds_read_b128 v[66:69], v22 offset:43520
	s_waitcnt lgkmcnt(0)
	v_mfma_f32_16x16x32_bf16 v[66:69], v[66:69], v[2:5], 0
	v_mfma_f32_16x16x32_bf16 v[66:69], v[70:73], v[6:9], v[66:69]
	ds_read_b128 v[70:73], v22 offset:43648
	s_waitcnt lgkmcnt(0)
	v_mfma_f32_16x16x32_bf16 v[66:69], v[70:73], v[10:13], v[66:69]
	ds_read_b128 v[70:73], v22 offset:43712
	s_waitcnt lgkmcnt(0)
	v_mfma_f32_16x16x32_bf16 v[66:69], v[70:73], v[14:17], v[66:69]
	ds_read_b128 v[70:73], v22 offset:47872
	s_waitcnt lgkmcnt(0)
	v_mfma_f32_16x16x32_bf16 v[70:73], v[70:73], v[2:5], 0
	v_mfma_f32_16x16x32_bf16 v[70:73], v[74:77], v[6:9], v[70:73]
	ds_read_b128 v[74:77], v22 offset:48000
	s_waitcnt lgkmcnt(0)
	v_mfma_f32_16x16x32_bf16 v[70:73], v[74:77], v[10:13], v[70:73]
	ds_read_b128 v[74:77], v22 offset:48064
	s_waitcnt lgkmcnt(0)
	v_mfma_f32_16x16x32_bf16 v[70:73], v[74:77], v[14:17], v[70:73]
	ds_read_b128 v[74:77], v22 offset:52224
	s_waitcnt lgkmcnt(0)
	v_mfma_f32_16x16x32_bf16 v[74:77], v[74:77], v[2:5], 0
	v_mfma_f32_16x16x32_bf16 v[74:77], v[78:81], v[6:9], v[74:77]
	ds_read_b128 v[78:81], v22 offset:52352
	s_waitcnt lgkmcnt(0)
	v_mfma_f32_16x16x32_bf16 v[74:77], v[78:81], v[10:13], v[74:77]
	ds_read_b128 v[78:81], v22 offset:52416
	s_waitcnt lgkmcnt(0)
	v_mfma_f32_16x16x32_bf16 v[74:77], v[78:81], v[14:17], v[74:77]
	ds_read_b128 v[78:81], v22 offset:56576
	s_waitcnt lgkmcnt(0)
	v_mfma_f32_16x16x32_bf16 v[78:81], v[78:81], v[2:5], 0
	v_mfma_f32_16x16x32_bf16 v[78:81], v[82:85], v[6:9], v[78:81]
	ds_read_b128 v[82:85], v22 offset:56704
	s_waitcnt lgkmcnt(0)
	v_mfma_f32_16x16x32_bf16 v[78:81], v[82:85], v[10:13], v[78:81]
	ds_read_b128 v[82:85], v22 offset:56768
	s_waitcnt lgkmcnt(0)
	v_mfma_f32_16x16x32_bf16 v[78:81], v[82:85], v[14:17], v[78:81]
	ds_read_b128 v[82:85], v22 offset:60928
	s_waitcnt lgkmcnt(0)
	v_mfma_f32_16x16x32_bf16 v[82:85], v[82:85], v[2:5], 0
	v_mfma_f32_16x16x32_bf16 v[82:85], v[86:89], v[6:9], v[82:85]
	ds_read_b128 v[86:89], v22 offset:61056
	s_waitcnt lgkmcnt(0)
	v_mfma_f32_16x16x32_bf16 v[82:85], v[86:89], v[10:13], v[82:85]
	ds_read_b128 v[86:89], v22 offset:61120
	s_waitcnt lgkmcnt(0)
	v_mfma_f32_16x16x32_bf16 v[82:85], v[86:89], v[14:17], v[82:85]
	ds_read_b128 v[86:89], v22 offset:65280
	s_waitcnt lgkmcnt(0)
	v_mfma_f32_16x16x32_bf16 v[2:5], v[86:89], v[2:5], 0
	ds_read_b128 v[86:89], v22 offset:65344
	s_waitcnt lgkmcnt(0)
	v_mfma_f32_16x16x32_bf16 v[2:5], v[86:89], v[6:9], v[2:5]
	ds_read_b128 v[6:9], v22 offset:65408
	s_waitcnt lgkmcnt(0)
	v_mfma_f32_16x16x32_bf16 v[2:5], v[6:9], v[10:13], v[2:5]
	ds_read_b128 v[6:9], v22 offset:65472
	s_waitcnt lgkmcnt(0)
; template <int HD, bool DIL>
; __device__ __forceinline__ void attn_compute(const bf16_t* Ks, const bf16_t* Vt, const bf16x8 (&qf)[HD / 32], int a, int quad, int fr,
;                                              const float* biasT, int kmin, f32x4 (&oacc)[HD / 16], float& mx_out, float& den_out) {
;     ...
;     float mx = -3.0e38f;
;     const float* tb = DIL ? (biasT + (127 - a + 4 * quad)) : nullptr;
; #pragma unroll
;     for (int nt = 0; nt < 16; ++nt)
; #pragma unroll
;         for (int j = 0; j < 4; ++j) {
;             float v = s[nt][j];
;             if (DIL) {
;                 v = v * 0.18033688011112042f + tb[16 * nt + j];
;                 if (nt < 8) v = kmin ? -1.0e30f : v;
;             }
;             s[nt][j] = v; mx = fmaxf(mx, v);
;         }
;     mx = fmaxf(mx, __shfl_xor(mx, 16)); mx = fmaxf(mx, __shfl_xor(mx, 32));
;     float sum = 0.f;
; #pragma unroll
;     for (int nt = 0; nt < 16; ++nt)
; #pragma unroll
;         for (int j = 0; j < 4; ++j) { const float pv = __builtin_amdgcn_exp2f(s[nt][j] - mx); s[nt][j] = pv; sum += pv; }
;     sum += __shfl_xor(sum, 16); sum += __shfl_xor(sum, 32);
	v_mfma_f32_16x16x32_bf16 v[2:5], v[6:9], v[14:17], v[2:5]
	v_max3_f32 v6, v18, s22, v19
	v_max3_f32 v6, v6, v20, v21
	v_max3_f32 v6, v6, v26, v27
	v_max3_f32 v6, v6, v28, v29
	v_max3_f32 v6, v6, v30, v31
	v_max3_f32 v6, v6, v32, v33
	v_max3_f32 v6, v6, v38, v39
	v_max3_f32 v6, v6, v40, v41
	v_max3_f32 v6, v6, v42, v43
	v_max3_f32 v6, v6, v44, v45
	v_max3_f32 v6, v6, v46, v47
	v_max3_f32 v6, v6, v48, v49
	v_max3_f32 v6, v6, v50, v51
	v_max3_f32 v6, v6, v52, v53
	v_max3_f32 v6, v6, v54, v55
	v_max3_f32 v6, v6, v56, v57
	v_max3_f32 v6, v6, v58, v59
	v_max3_f32 v6, v6, v60, v61
	v_max3_f32 v6, v6, v62, v63
	v_max3_f32 v6, v6, v64, v65
	v_max3_f32 v6, v6, v66, v67
	v_max3_f32 v6, v6, v68, v69
	v_max3_f32 v6, v6, v70, v71
	v_max3_f32 v6, v6, v72, v73
	v_max3_f32 v6, v6, v74, v75
	v_max3_f32 v6, v6, v76, v77
	v_max3_f32 v6, v6, v78, v79
	v_max3_f32 v6, v6, v80, v81
	v_max3_f32 v6, v6, v82, v83
	v_max3_f32 v6, v6, v84, v85
	v_max3_f32 v6, v6, v2, v3
	v_max3_f32 v6, v6, v4, v5
	ds_bpermute_b32 v7, v25, v6
	s_waitcnt lgkmcnt(0)
	v_max_f32_e32 v7, v7, v7
	v_max_f32_e32 v6, v6, v7
	ds_bpermute_b32 v7, v34, v6
	s_waitcnt lgkmcnt(0)
	v_max_f32_e32 v7, v7, v7
	v_max_f32_e32 v6, v6, v7
	v_sub_f32_e32 v7, v18, v6
	v_exp_f32_e32 v7, v7
	v_sub_f32_e32 v9, v19, v6
	v_exp_f32_e32 v9, v9
	v_sub_f32_e32 v10, v20, v6
	v_exp_f32_e32 v10, v10
	v_sub_f32_e32 v11, v21, v6
	v_exp_f32_e32 v11, v11
	v_sub_f32_e32 v12, v26, v6
	v_add_f32_e32 v8, 0, v7
	v_exp_f32_e32 v12, v12
	v_sub_f32_e32 v13, v27, v6
	v_add_f32_e32 v8, v9, v8
	v_exp_f32_e32 v13, v13
	v_sub_f32_e32 v14, v28, v6
	v_add_f32_e32 v8, v10, v8
	v_exp_f32_e32 v14, v14
	v_sub_f32_e32 v15, v29, v6
	v_add_f32_e32 v8, v11, v8
	v_exp_f32_e32 v15, v15
	v_sub_f32_e32 v16, v30, v6
	v_add_f32_e32 v8, v12, v8
	v_exp_f32_e32 v35, v16
	v_sub_f32_e32 v16, v31, v6
	v_add_f32_e32 v8, v13, v8
	v_exp_f32_e32 v86, v16
	v_sub_f32_e32 v16, v32, v6
	v_add_f32_e32 v8, v14, v8
	v_exp_f32_e32 v87, v16
	v_sub_f32_e32 v16, v33, v6
	v_add_f32_e32 v8, v15, v8
	v_exp_f32_e32 v88, v16
	v_sub_f32_e32 v16, v38, v6
	v_add_f32_e32 v8, v35, v8
	v_exp_f32_e32 v89, v16
	v_sub_f32_e32 v16, v39, v6
	v_add_f32_e32 v8, v86, v8
	v_exp_f32_e32 v90, v16
	v_sub_f32_e32 v16, v40, v6
	v_add_f32_e32 v8, v87, v8
	v_exp_f32_e32 v91, v16
	v_sub_f32_e32 v16, v41, v6
	v_add_f32_e32 v8, v88, v8
	v_exp_f32_e32 v92, v16
	v_sub_f32_e32 v16, v42, v6
	v_add_f32_e32 v8, v89, v8
	v_exp_f32_e32 v93, v16
	v_sub_f32_e32 v16, v43, v6
	v_add_f32_e32 v8, v90, v8
	v_exp_f32_e32 v94, v16
	v_sub_f32_e32 v16, v44, v6
	v_add_f32_e32 v8, v91, v8
	v_exp_f32_e32 v95, v16
	v_sub_f32_e32 v16, v45, v6
	v_add_f32_e32 v8, v92, v8
	v_exp_f32_e32 v96, v16
	v_sub_f32_e32 v16, v46, v6
	v_add_f32_e32 v8, v93, v8
	v_exp_f32_e32 v46, v16
	v_sub_f32_e32 v16, v47, v6
	v_add_f32_e32 v8, v94, v8
	v_exp_f32_e32 v47, v16
	v_sub_f32_e32 v16, v48, v6
	v_add_f32_e32 v8, v95, v8
	v_exp_f32_e32 v48, v16
	v_sub_f32_e32 v16, v49, v6
	v_add_f32_e32 v8, v96, v8
	v_exp_f32_e32 v49, v16
	v_sub_f32_e32 v16, v50, v6
	v_add_f32_e32 v8, v46, v8
	v_exp_f32_e32 v50, v16
	v_sub_f32_e32 v16, v51, v6
	v_add_f32_e32 v8, v47, v8
	v_exp_f32_e32 v51, v16
	v_sub_f32_e32 v16, v52, v6
	v_add_f32_e32 v8, v48, v8
	v_exp_f32_e32 v52, v16
	v_sub_f32_e32 v16, v53, v6
	v_add_f32_e32 v8, v49, v8
	v_exp_f32_e32 v53, v16
	v_sub_f32_e32 v16, v54, v6
	v_add_f32_e32 v8, v50, v8
	v_exp_f32_e32 v54, v16
	v_sub_f32_e32 v16, v55, v6
	v_add_f32_e32 v8, v51, v8
	v_exp_f32_e32 v55, v16
	v_sub_f32_e32 v16, v56, v6
	v_add_f32_e32 v8, v52, v8
	v_exp_f32_e32 v56, v16
	v_sub_f32_e32 v16, v57, v6
	v_add_f32_e32 v8, v53, v8
	v_exp_f32_e32 v57, v16
	v_sub_f32_e32 v16, v58, v6
	v_add_f32_e32 v8, v54, v8
	v_exp_f32_e32 v58, v16
	v_sub_f32_e32 v16, v59, v6
	v_add_f32_e32 v8, v55, v8
	v_exp_f32_e32 v59, v16
	v_sub_f32_e32 v16, v60, v6
	v_add_f32_e32 v8, v56, v8
	v_exp_f32_e32 v60, v16
	v_sub_f32_e32 v16, v61, v6
	v_add_f32_e32 v8, v57, v8
	v_exp_f32_e32 v61, v16
	v_sub_f32_e32 v16, v62, v6
	v_add_f32_e32 v8, v58, v8
	v_exp_f32_e32 v62, v16
	v_sub_f32_e32 v16, v63, v6
	v_add_f32_e32 v8, v59, v8
	v_exp_f32_e32 v63, v16
	v_sub_f32_e32 v16, v64, v6
	v_add_f32_e32 v8, v60, v8
	v_exp_f32_e32 v64, v16
	v_sub_f32_e32 v16, v65, v6
	v_add_f32_e32 v8, v61, v8
	v_exp_f32_e32 v65, v16
	v_sub_f32_e32 v16, v66, v6
	v_add_f32_e32 v8, v62, v8
	v_exp_f32_e32 v66, v16
	v_sub_f32_e32 v16, v67, v6
	v_add_f32_e32 v8, v63, v8
	v_exp_f32_e32 v67, v16
	v_sub_f32_e32 v16, v68, v6
	v_add_f32_e32 v8, v64, v8
	v_exp_f32_e32 v68, v16
	v_sub_f32_e32 v16, v69, v6
	v_add_f32_e32 v8, v65, v8
	v_exp_f32_e32 v69, v16
	v_sub_f32_e32 v16, v70, v6
	v_add_f32_e32 v8, v66, v8
	v_exp_f32_e32 v70, v16
	v_sub_f32_e32 v16, v71, v6
	v_add_f32_e32 v8, v67, v8
	v_exp_f32_e32 v71, v16
	v_sub_f32_e32 v16, v72, v6
	v_add_f32_e32 v8, v68, v8
	v_exp_f32_e32 v72, v16
	v_sub_f32_e32 v16, v73, v6
	v_add_f32_e32 v8, v69, v8
	v_exp_f32_e32 v73, v16
	v_sub_f32_e32 v16, v74, v6
	v_add_f32_e32 v8, v70, v8
	v_exp_f32_e32 v74, v16
	v_sub_f32_e32 v16, v75, v6
	v_add_f32_e32 v8, v71, v8
	v_exp_f32_e32 v75, v16
	v_sub_f32_e32 v16, v76, v6
	v_add_f32_e32 v8, v72, v8
	v_exp_f32_e32 v76, v16
	v_sub_f32_e32 v16, v77, v6
	v_add_f32_e32 v8, v73, v8
	v_exp_f32_e32 v77, v16
	v_sub_f32_e32 v16, v78, v6
	v_add_f32_e32 v8, v74, v8
	v_exp_f32_e32 v78, v16
	v_sub_f32_e32 v16, v79, v6
	v_add_f32_e32 v8, v75, v8
	v_exp_f32_e32 v79, v16
	v_sub_f32_e32 v16, v80, v6
	v_add_f32_e32 v8, v76, v8
	v_exp_f32_e32 v80, v16
	v_sub_f32_e32 v16, v81, v6
	v_add_f32_e32 v8, v77, v8
	v_exp_f32_e32 v81, v16
	v_sub_f32_e32 v16, v82, v6
	v_add_f32_e32 v8, v78, v8
	v_exp_f32_e32 v82, v16
	v_sub_f32_e32 v16, v83, v6
	v_add_f32_e32 v8, v79, v8
	v_exp_f32_e32 v83, v16
	v_sub_f32_e32 v16, v84, v6
	v_add_f32_e32 v8, v80, v8
	v_exp_f32_e32 v84, v16
	v_sub_f32_e32 v16, v85, v6
	v_add_f32_e32 v8, v81, v8
	v_exp_f32_e32 v85, v16
	v_sub_f32_e32 v2, v2, v6
	v_add_f32_e32 v8, v82, v8
	v_exp_f32_e32 v97, v2
	v_sub_f32_e32 v3, v3, v6
	v_add_f32_e32 v8, v83, v8
	v_exp_f32_e32 v98, v3
	v_sub_f32_e32 v3, v4, v6
	v_add_f32_e32 v8, v84, v8
	v_exp_f32_e32 v99, v3
	v_sub_f32_e32 v3, v5, v6
	v_add_f32_e32 v8, v85, v8
	v_exp_f32_e32 v100, v3
	v_add_f32_e32 v2, v97, v8
	v_add_f32_e32 v2, v98, v2
	v_add_f32_e32 v2, v99, v2
	v_add_f32_e32 v2, v100, v2
	ds_bpermute_b32 v3, v25, v2
	v_mul_u32_u24_e32 v6, 0x218, v24
	v_add3_u32 v102, s8, v0, v6
	v_add_u32_e32 v103, 0x2000, v102
	v_add_u32_e32 v104, 0x4000, v102
	s_waitcnt lgkmcnt(0)
; __device__ __forceinline__ unsigned pk2(float lo, float hi) { const hf32x2 v = {lo, hi}; return __builtin_bit_cast(unsigned, __builtin_convertvector(v, hbf16x2)); }
; template <int HD, bool DIL>
; __device__ __forceinline__ void attn_compute(const bf16_t* Ks, const bf16_t* Vt, const bf16x8 (&qf)[HD / 32], int a, int quad, int fr,
;                                              const float* biasT, int kmin, f32x4 (&oacc)[HD / 16], float& mx_out, float& den_out) {
;     ...
;     sum += __shfl_xor(sum, 16); sum += __shfl_xor(sum, 32);
; #pragma unroll
;     for (int dt = 0; dt < HD / 16; ++dt) oacc[dt] = (f32x4){0.f, 0.f, 0.f, 0.f};
; #pragma unroll
;     for (int k2 = 0; k2 < 8; ++k2) {
;         u32x4 pp; pp.x = pk2(s[2 * k2][0], s[2 * k2][1]); pp.y = pk2(s[2 * k2][2], s[2 * k2][3]); pp.z = pk2(s[2 * k2 + 1][0], s[2 * k2 + 1][1]); pp.w = pk2(s[2 * k2 + 1][2], s[2 * k2 + 1][3]);
;         const bf16x8 pf = __builtin_bit_cast(bf16x8, pp);
; #pragma unroll
;         for (int dt = 0; dt < HD / 16; ++dt) {
;             const bf16_t* vp = Vt + (16 * dt + fr) * VS + 32 * k2 + quad * 4;
;             const u32x2 lo = *(const u32x2*)vp, hi = *(const u32x2*)(vp + 16);
;             u32x4 vv; vv.x = lo.x; vv.y = lo.y; vv.z = hi.x; vv.w = hi.y;
;             oacc[dt] = __builtin_amdgcn_mfma_f32_16x16x32_bf16(__builtin_bit_cast(bf16x8, vv), pf, oacc[dt], 0, 0, 0);
;         }
;     }
	v_add_f32_e32 v101, v2, v3
	v_cvt_pk_bf16_f32 v2, v7, v9
	ds_read2_b64 v[6:9], v102 offset1:4
	v_add_u32_e32 v105, 0x6000, v102
	v_add_u32_e32 v106, 0x8000, v102
	v_add_u32_e32 v107, 0xa000, v102
	v_add_u32_e32 v108, 0xc800, v102
	v_add_u32_e32 v109, 0xe800, v102
	v_cvt_pk_bf16_f32 v3, v10, v11
	v_cvt_pk_bf16_f32 v4, v12, v13
	v_cvt_pk_bf16_f32 v5, v14, v15
	ds_read2_b64 v[10:13], v103 offset0:48 offset1:52
	ds_read2_b64 v[14:17], v104 offset0:96 offset1:100
	ds_read2_b64 v[18:21], v105 offset0:144 offset1:148
	ds_read2_b64 v[22:25], v106 offset0:192 offset1:196
	ds_read2_b64 v[26:29], v107 offset0:240 offset1:244
	ds_read2_b64 v[30:33], v108 offset0:32 offset1:36
	ds_read2_b64 v[38:41], v109 offset0:80 offset1:84
	ds_read2_b64 v[42:45], v102 offset0:8 offset1:12
	s_waitcnt lgkmcnt(8)
	v_mfma_f32_16x16x32_bf16 v[6:9], v[6:9], v[2:5], 0
	ds_bpermute_b32 v34, v34, v101
	s_waitcnt lgkmcnt(0)
	v_add_f32_e32 v34, v101, v34
	v_mfma_f32_16x16x32_bf16 v[10:13], v[10:13], v[2:5], 0
	v_mfma_f32_16x16x32_bf16 v[14:17], v[14:17], v[2:5], 0
	v_mfma_f32_16x16x32_bf16 v[18:21], v[18:21], v[2:5], 0
	v_mfma_f32_16x16x32_bf16 v[22:25], v[22:25], v[2:5], 0
	v_mfma_f32_16x16x32_bf16 v[26:29], v[26:29], v[2:5], 0
	v_mfma_f32_16x16x32_bf16 v[30:33], v[30:33], v[2:5], 0
	v_mfma_f32_16x16x32_bf16 v[2:5], v[38:41], v[2:5], 0
	v_cvt_pk_bf16_f32 v38, v35, v86
	v_cvt_pk_bf16_f32 v39, v87, v88
	v_cvt_pk_bf16_f32 v40, v89, v90
	v_cvt_pk_bf16_f32 v41, v91, v92
	v_add_u32_e32 v35, 0xa800, v102
	s_nop 0
	v_mfma_f32_16x16x32_bf16 v[6:9], v[42:45], v[38:41], v[6:9]
	ds_read2_b64 v[42:45], v103 offset0:56 offset1:60
	s_waitcnt lgkmcnt(0)
	v_mfma_f32_16x16x32_bf16 v[10:13], v[42:45], v[38:41], v[10:13]
	ds_read2_b64 v[42:45], v104 offset0:104 offset1:108
	s_waitcnt lgkmcnt(0)
	v_mfma_f32_16x16x32_bf16 v[14:17], v[42:45], v[38:41], v[14:17]
	ds_read2_b64 v[42:45], v105 offset0:152 offset1:156
	s_waitcnt lgkmcnt(0)
	v_mfma_f32_16x16x32_bf16 v[18:21], v[42:45], v[38:41], v[18:21]
	ds_read2_b64 v[42:45], v106 offset0:200 offset1:204
	s_waitcnt lgkmcnt(0)
	v_mfma_f32_16x16x32_bf16 v[22:25], v[42:45], v[38:41], v[22:25]
	ds_read2_b64 v[42:45], v107 offset0:248 offset1:252
	s_waitcnt lgkmcnt(0)
	v_mfma_f32_16x16x32_bf16 v[26:29], v[42:45], v[38:41], v[26:29]
	ds_read2_b64 v[42:45], v108 offset0:40 offset1:44
	s_waitcnt lgkmcnt(0)
	v_mfma_f32_16x16x32_bf16 v[30:33], v[42:45], v[38:41], v[30:33]
	ds_read2_b64 v[42:45], v109 offset0:88 offset1:92
	s_waitcnt lgkmcnt(0)
	v_mfma_f32_16x16x32_bf16 v[2:5], v[42:45], v[38:41], v[2:5]
	ds_read2_b64 v[42:45], v102 offset0:16 offset1:20
	v_cvt_pk_bf16_f32 v38, v93, v94
	v_cvt_pk_bf16_f32 v39, v95, v96
	v_cvt_pk_bf16_f32 v40, v46, v47
	v_cvt_pk_bf16_f32 v41, v48, v49
	s_waitcnt lgkmcnt(0)
	s_nop 0
	v_mfma_f32_16x16x32_bf16 v[6:9], v[42:45], v[38:41], v[6:9]
	ds_read2_b64 v[42:45], v103 offset0:64 offset1:68
	s_waitcnt lgkmcnt(0)
	v_mfma_f32_16x16x32_bf16 v[10:13], v[42:45], v[38:41], v[10:13]
	ds_read2_b64 v[42:45], v104 offset0:112 offset1:116
	s_waitcnt lgkmcnt(0)
	v_mfma_f32_16x16x32_bf16 v[14:17], v[42:45], v[38:41], v[14:17]
	ds_read2_b64 v[42:45], v105 offset0:160 offset1:164
	s_waitcnt lgkmcnt(0)
	v_mfma_f32_16x16x32_bf16 v[18:21], v[42:45], v[38:41], v[18:21]
	ds_read2_b64 v[42:45], v106 offset0:208 offset1:212
	s_waitcnt lgkmcnt(0)
	v_mfma_f32_16x16x32_bf16 v[22:25], v[42:45], v[38:41], v[22:25]
	ds_read2_b64 v[42:45], v35 offset1:4
	s_waitcnt lgkmcnt(0)
	v_mfma_f32_16x16x32_bf16 v[26:29], v[42:45], v[38:41], v[26:29]
	ds_read2_b64 v[42:45], v108 offset0:48 offset1:52
	s_waitcnt lgkmcnt(0)
	v_mfma_f32_16x16x32_bf16 v[30:33], v[42:45], v[38:41], v[30:33]
	ds_read2_b64 v[42:45], v109 offset0:96 offset1:100
	s_waitcnt lgkmcnt(0)
	v_mfma_f32_16x16x32_bf16 v[2:5], v[42:45], v[38:41], v[2:5]
	ds_read2_b64 v[42:45], v102 offset0:24 offset1:28
	v_cvt_pk_bf16_f32 v38, v50, v51
	v_cvt_pk_bf16_f32 v39, v52, v53
	v_cvt_pk_bf16_f32 v40, v54, v55
	v_cvt_pk_bf16_f32 v41, v56, v57
	s_waitcnt lgkmcnt(0)
	s_nop 0
	v_mfma_f32_16x16x32_bf16 v[6:9], v[42:45], v[38:41], v[6:9]
	ds_read2_b64 v[42:45], v103 offset0:72 offset1:76
	s_waitcnt lgkmcnt(0)
	v_mfma_f32_16x16x32_bf16 v[10:13], v[42:45], v[38:41], v[10:13]
	ds_read2_b64 v[42:45], v104 offset0:120 offset1:124
	s_waitcnt lgkmcnt(0)
	v_mfma_f32_16x16x32_bf16 v[14:17], v[42:45], v[38:41], v[14:17]
	ds_read2_b64 v[42:45], v105 offset0:168 offset1:172
	s_waitcnt lgkmcnt(0)
	v_mfma_f32_16x16x32_bf16 v[18:21], v[42:45], v[38:41], v[18:21]
	ds_read2_b64 v[42:45], v106 offset0:216 offset1:220
	s_waitcnt lgkmcnt(0)
	v_mfma_f32_16x16x32_bf16 v[22:25], v[42:45], v[38:41], v[22:25]
	ds_read2_b64 v[42:45], v35 offset0:8 offset1:12
	s_waitcnt lgkmcnt(0)
	v_mfma_f32_16x16x32_bf16 v[26:29], v[42:45], v[38:41], v[26:29]
	ds_read2_b64 v[42:45], v108 offset0:56 offset1:60
	s_waitcnt lgkmcnt(0)
	v_mfma_f32_16x16x32_bf16 v[30:33], v[42:45], v[38:41], v[30:33]
	ds_read2_b64 v[42:45], v109 offset0:104 offset1:108
	s_waitcnt lgkmcnt(0)
	v_mfma_f32_16x16x32_bf16 v[2:5], v[42:45], v[38:41], v[2:5]
	ds_read2_b64 v[42:45], v102 offset0:32 offset1:36
	v_cvt_pk_bf16_f32 v38, v58, v59
	v_cvt_pk_bf16_f32 v39, v60, v61
	v_cvt_pk_bf16_f32 v40, v62, v63
	v_cvt_pk_bf16_f32 v41, v64, v65
	s_waitcnt lgkmcnt(0)
	s_nop 0
	v_mfma_f32_16x16x32_bf16 v[6:9], v[42:45], v[38:41], v[6:9]
	ds_read2_b64 v[42:45], v103 offset0:80 offset1:84
	s_waitcnt lgkmcnt(0)
	v_mfma_f32_16x16x32_bf16 v[10:13], v[42:45], v[38:41], v[10:13]
	ds_read2_b64 v[42:45], v104 offset0:128 offset1:132
	s_waitcnt lgkmcnt(0)
	v_mfma_f32_16x16x32_bf16 v[14:17], v[42:45], v[38:41], v[14:17]
	ds_read2_b64 v[42:45], v105 offset0:176 offset1:180
	s_waitcnt lgkmcnt(0)
; __device__ __forceinline__ unsigned pk2(float lo, float hi) { const hf32x2 v = {lo, hi}; return __builtin_bit_cast(unsigned, __builtin_convertvector(v, hbf16x2)); }
; template <int HD, bool DIL>
; __device__ __forceinline__ void attn_compute(const bf16_t* Ks, const bf16_t* Vt, const bf16x8 (&qf)[HD / 32], int a, int quad, int fr,
;                                              const float* biasT, int kmin, f32x4 (&oacc)[HD / 16], float& mx_out, float& den_out) {
;     ...
;     for (int k2 = 0; k2 < 8; ++k2) {
;         u32x4 pp; pp.x = pk2(s[2 * k2][0], s[2 * k2][1]); pp.y = pk2(s[2 * k2][2], s[2 * k2][3]); pp.z = pk2(s[2 * k2 + 1][0], s[2 * k2 + 1][1]); pp.w = pk2(s[2 * k2 + 1][2], s[2 * k2 + 1][3]);
;         const bf16x8 pf = __builtin_bit_cast(bf16x8, pp);
; #pragma unroll
;         for (int dt = 0; dt < HD / 16; ++dt) {
;             const bf16_t* vp = Vt + (16 * dt + fr) * VS + 32 * k2 + quad * 4;
;             const u32x2 lo = *(const u32x2*)vp, hi = *(const u32x2*)(vp + 16);
;             u32x4 vv; vv.x = lo.x; vv.y = lo.y; vv.z = hi.x; vv.w = hi.y;
;             oacc[dt] = __builtin_amdgcn_mfma_f32_16x16x32_bf16(__builtin_bit_cast(bf16x8, vv), pf, oacc[dt], 0, 0, 0);
;         }
;     }
; __device__ __forceinline__ void cross_attn_unit(PP p, unsigned char* shm, int u, int l) {
;     ...
;     const float inv = 1.0f / den;
;     bf16_t* ox = (bf16_t*)(p->ws + WS_OX) + rowq * 512 + xh * 128 + quad * 4;
; #pragma unroll
;     for (int dt = 0; dt < 8; ++dt) { u32x2 o; o.x = pk2(oacc[dt][0] * inv, oacc[dt][1] * inv); o.y = pk2(oacc[dt][2] * inv, oacc[dt][3] * inv); *(u32x2*)(ox + 16 * dt) = o; }
;     __syncthreads();
	v_mfma_f32_16x16x32_bf16 v[18:21], v[42:45], v[38:41], v[18:21]
	ds_read2_b64 v[42:45], v106 offset0:224 offset1:228
	s_waitcnt lgkmcnt(0)
	v_mfma_f32_16x16x32_bf16 v[22:25], v[42:45], v[38:41], v[22:25]
	ds_read2_b64 v[42:45], v35 offset0:16 offset1:20
	s_waitcnt lgkmcnt(0)
	v_mfma_f32_16x16x32_bf16 v[26:29], v[42:45], v[38:41], v[26:29]
	ds_read2_b64 v[42:45], v108 offset0:64 offset1:68
	s_waitcnt lgkmcnt(0)
	v_mfma_f32_16x16x32_bf16 v[30:33], v[42:45], v[38:41], v[30:33]
	ds_read2_b64 v[42:45], v109 offset0:112 offset1:116
	s_waitcnt lgkmcnt(0)
	v_mfma_f32_16x16x32_bf16 v[2:5], v[42:45], v[38:41], v[2:5]
	ds_read2_b64 v[42:45], v102 offset0:40 offset1:44
	v_cvt_pk_bf16_f32 v38, v66, v67
	v_cvt_pk_bf16_f32 v39, v68, v69
	v_cvt_pk_bf16_f32 v40, v70, v71
	v_cvt_pk_bf16_f32 v41, v72, v73
	s_waitcnt lgkmcnt(0)
	s_nop 0
	v_mfma_f32_16x16x32_bf16 v[6:9], v[42:45], v[38:41], v[6:9]
	ds_read2_b64 v[42:45], v103 offset0:88 offset1:92
	s_waitcnt lgkmcnt(0)
	v_mfma_f32_16x16x32_bf16 v[10:13], v[42:45], v[38:41], v[10:13]
	ds_read2_b64 v[42:45], v104 offset0:136 offset1:140
	s_waitcnt lgkmcnt(0)
	v_mfma_f32_16x16x32_bf16 v[14:17], v[42:45], v[38:41], v[14:17]
	ds_read2_b64 v[42:45], v105 offset0:184 offset1:188
	s_waitcnt lgkmcnt(0)
	v_mfma_f32_16x16x32_bf16 v[18:21], v[42:45], v[38:41], v[18:21]
	ds_read2_b64 v[42:45], v106 offset0:232 offset1:236
	s_waitcnt lgkmcnt(0)
	v_mfma_f32_16x16x32_bf16 v[22:25], v[42:45], v[38:41], v[22:25]
	ds_read2_b64 v[42:45], v35 offset0:24 offset1:28
	s_waitcnt lgkmcnt(0)
	v_mfma_f32_16x16x32_bf16 v[26:29], v[42:45], v[38:41], v[26:29]
	ds_read2_b64 v[42:45], v108 offset0:72 offset1:76
	s_waitcnt lgkmcnt(0)
	v_mfma_f32_16x16x32_bf16 v[30:33], v[42:45], v[38:41], v[30:33]
	ds_read2_b64 v[42:45], v109 offset0:120 offset1:124
	s_waitcnt lgkmcnt(0)
	v_mfma_f32_16x16x32_bf16 v[2:5], v[42:45], v[38:41], v[2:5]
	ds_read2_b64 v[42:45], v102 offset0:48 offset1:52
	v_cvt_pk_bf16_f32 v38, v74, v75
	v_cvt_pk_bf16_f32 v39, v76, v77
	v_cvt_pk_bf16_f32 v40, v78, v79
	v_cvt_pk_bf16_f32 v41, v80, v81
	s_waitcnt lgkmcnt(0)
	s_nop 0
	v_mfma_f32_16x16x32_bf16 v[6:9], v[42:45], v[38:41], v[6:9]
	ds_read2_b64 v[42:45], v103 offset0:96 offset1:100
	s_waitcnt lgkmcnt(0)
	v_mfma_f32_16x16x32_bf16 v[10:13], v[42:45], v[38:41], v[10:13]
	ds_read2_b64 v[42:45], v104 offset0:144 offset1:148
	s_waitcnt lgkmcnt(0)
	v_mfma_f32_16x16x32_bf16 v[14:17], v[42:45], v[38:41], v[14:17]
	ds_read2_b64 v[42:45], v105 offset0:192 offset1:196
	s_waitcnt lgkmcnt(0)
	v_mfma_f32_16x16x32_bf16 v[18:21], v[42:45], v[38:41], v[18:21]
	ds_read2_b64 v[42:45], v106 offset0:240 offset1:244
	s_waitcnt lgkmcnt(0)
	v_mfma_f32_16x16x32_bf16 v[42:45], v[42:45], v[38:41], v[22:25]
	s_nop 2
	ds_read2_b64 v[22:25], v35 offset0:32 offset1:36
	s_waitcnt lgkmcnt(0)
	v_mfma_f32_16x16x32_bf16 v[46:49], v[22:25], v[38:41], v[26:29]
	ds_read2_b64 v[22:25], v108 offset0:80 offset1:84
	s_waitcnt lgkmcnt(0)
	v_mfma_f32_16x16x32_bf16 v[50:53], v[22:25], v[38:41], v[30:33]
	ds_read2_b64 v[22:25], v109 offset0:128 offset1:132
	s_waitcnt lgkmcnt(0)
	v_mfma_f32_16x16x32_bf16 v[2:5], v[22:25], v[38:41], v[2:5]
	ds_read2_b64 v[22:25], v102 offset0:56 offset1:60
	v_cvt_pk_bf16_f32 v38, v82, v83
	v_cvt_pk_bf16_f32 v39, v84, v85
	v_cvt_pk_bf16_f32 v40, v97, v98
	v_cvt_pk_bf16_f32 v41, v99, v100
	s_waitcnt lgkmcnt(0)
	s_nop 0
	v_mfma_f32_16x16x32_bf16 v[30:33], v[22:25], v[38:41], v[6:9]
	s_nop 2
	ds_read2_b64 v[6:9], v103 offset0:104 offset1:108
	s_waitcnt lgkmcnt(0)
	v_mfma_f32_16x16x32_bf16 v[26:29], v[6:9], v[38:41], v[10:13]
	ds_read2_b64 v[6:9], v104 offset0:152 offset1:156
	s_waitcnt lgkmcnt(0)
	v_mfma_f32_16x16x32_bf16 v[22:25], v[6:9], v[38:41], v[14:17]
	ds_read2_b64 v[6:9], v105 offset0:200 offset1:204
	s_waitcnt lgkmcnt(0)
	v_mfma_f32_16x16x32_bf16 v[18:21], v[6:9], v[38:41], v[18:21]
	ds_read2_b64 v[6:9], v106 offset0:248 offset1:252
	s_waitcnt lgkmcnt(0)
	v_mfma_f32_16x16x32_bf16 v[14:17], v[6:9], v[38:41], v[42:45]
	ds_read2_b64 v[6:9], v35 offset0:40 offset1:44
	s_nop 1
	ds_read2_b64 v[42:45], v109 offset0:136 offset1:140
	v_div_scale_f32 v35, s[8:9], v34, v34, 1.0
	s_waitcnt lgkmcnt(1)
	v_mfma_f32_16x16x32_bf16 v[10:13], v[6:9], v[38:41], v[46:49]
	ds_read2_b64 v[6:9], v108 offset0:88 offset1:92
	s_mov_b64 s[8:9], 0x286c0000
	s_waitcnt lgkmcnt(0)
	v_mfma_f32_16x16x32_bf16 v[6:9], v[6:9], v[38:41], v[50:53]
	v_mfma_f32_16x16x32_bf16 v[2:5], v[42:45], v[38:41], v[2:5]
	v_rcp_f32_e32 v38, v35
	s_nop 0
	v_fma_f32 v39, -v35, v38, 1.0
	v_fmac_f32_e32 v38, v39, v38
	v_div_scale_f32 v39, vcc, 1.0, v34, 1.0
	v_mul_f32_e32 v40, v39, v38
	v_fma_f32 v41, -v35, v40, v39
	v_fmac_f32_e32 v40, v41, v38
	v_fma_f32 v35, -v35, v40, v39
	v_div_fmas_f32 v35, v35, v38, v40
	v_div_fixup_f32 v34, v35, v34, 1.0
	v_lshl_add_u64 v[38:39], v[36:37], 0, s[8:9]
	v_pk_mul_f32 v[30:31], v[30:31], v[34:35] op_sel_hi:[1,0]
	v_pk_mul_f32 v[32:33], v[32:33], v[34:35] op_sel_hi:[1,0]
	s_mov_b32 s8, 0x286c0000
	v_cvt_pk_bf16_f32 v30, v30, v31
	v_cvt_pk_bf16_f32 v31, v32, v33
	v_add_co_u32_e32 v32, vcc, s8, v36
	v_pk_mul_f32 v[26:27], v[26:27], v[34:35] op_sel_hi:[1,0]
	v_pk_mul_f32 v[28:29], v[28:29], v[34:35] op_sel_hi:[1,0]
	v_pk_mul_f32 v[22:23], v[22:23], v[34:35] op_sel_hi:[1,0]
	v_pk_mul_f32 v[24:25], v[24:25], v[34:35] op_sel_hi:[1,0]
	v_pk_mul_f32 v[18:19], v[18:19], v[34:35] op_sel_hi:[1,0]
	v_pk_mul_f32 v[20:21], v[20:21], v[34:35] op_sel_hi:[1,0]
	v_pk_mul_f32 v[14:15], v[14:15], v[34:35] op_sel_hi:[1,0]
	v_pk_mul_f32 v[16:17], v[16:17], v[34:35] op_sel_hi:[1,0]
	v_pk_mul_f32 v[10:11], v[10:11], v[34:35] op_sel_hi:[1,0]
	v_pk_mul_f32 v[12:13], v[12:13], v[34:35] op_sel_hi:[1,0]
	v_pk_mul_f32 v[6:7], v[6:7], v[34:35] op_sel_hi:[1,0]
	v_pk_mul_f32 v[8:9], v[8:9], v[34:35] op_sel_hi:[1,0]
	v_pk_mul_f32 v[2:3], v[2:3], v[34:35] op_sel_hi:[1,0]
	v_pk_mul_f32 v[4:5], v[4:5], v[34:35] op_sel_hi:[1,0]
	v_addc_co_u32_e32 v33, vcc, 0, v37, vcc
	v_cvt_pk_bf16_f32 v26, v26, v27
	v_cvt_pk_bf16_f32 v27, v28, v29
	v_cvt_pk_bf16_f32 v22, v22, v23
	v_cvt_pk_bf16_f32 v23, v24, v25
	v_cvt_pk_bf16_f32 v18, v18, v19
	v_cvt_pk_bf16_f32 v19, v20, v21
	v_cvt_pk_bf16_f32 v14, v14, v15
	v_cvt_pk_bf16_f32 v15, v16, v17
	v_cvt_pk_bf16_f32 v10, v10, v11
	v_cvt_pk_bf16_f32 v11, v12, v13
	v_cvt_pk_bf16_f32 v6, v6, v7
	v_cvt_pk_bf16_f32 v7, v8, v9
	v_cvt_pk_bf16_f32 v2, v2, v3
	v_cvt_pk_bf16_f32 v3, v4, v5
	global_store_dwordx2 v[32:33], v[30:31], off
	global_store_dwordx2 v[38:39], v[26:27], off offset:32
	global_store_dwordx2 v[38:39], v[22:23], off offset:64
	global_store_dwordx2 v[38:39], v[18:19], off offset:96
	global_store_dwordx2 v[38:39], v[14:15], off offset:128
	global_store_dwordx2 v[38:39], v[10:11], off offset:160
	global_store_dwordx2 v[38:39], v[6:7], off offset:192
	global_store_dwordx2 v[38:39], v[2:3], off offset:224
	s_barrier
	s_cbranch_scc0 .LBB0_1180
